# FF1 GEMM K-loop: LDS-DMA staging rebalanced 4+4 per sub-phase (A tile staged in SP1, B tile in SP2), vmcnt(6) in SP2
# speedup vs baseline: 1.0025x; 1.0025x over previous
.LBB0_202:
	v_mov_b32_e32 v135, v1
	v_lshl_add_u64 v[26:27], s[58:59], 0, v[134:135]
	v_mov_b32_e32 v131, v1
	v_lshl_add_u64 v[28:29], s[58:59], 0, v[130:131]
	v_mov_b32_e32 v137, v1
	s_add_i32 m0, s27, 0x18000
	v_lshl_add_u64 v[26:27], v[26:27], 0, s[24:25]
	v_lshl_add_u64 v[34:35], s[56:57], 0, v[136:137]
	v_mov_b32_e32 v133, v1
	s_waitcnt vmcnt(2)
	s_barrier
	global_load_lds_dwordx4 v[26:27], off
	v_lshl_add_u64 v[26:27], v[28:29], 0, s[24:25]
	s_add_i32 m0, s27, 0x1a000
	s_add_i32 s31, s27, 0x8000
	v_lshl_add_u64 v[36:37], s[56:57], 0, v[132:133]
	global_load_lds_dwordx4 v[26:27], off
	s_add_i32 s53, s27, 0xa000
	v_lshl_add_u64 v[30:31], s[44:45], 0, v[134:135]
	v_lshl_add_u64 v[32:33], s[44:45], 0, v[130:131]
	s_add_i32 m0, s27, 0x1c000
	v_lshl_add_u64 v[26:27], v[30:31], 0, s[24:25]
	global_load_lds_dwordx4 v[26:27], off
	v_lshl_add_u64 v[26:27], v[32:33], 0, s[24:25]
	s_add_i32 m0, s27, 0x1e000
	s_andn2_b64 vcc, exec, s[38:39]
	global_load_lds_dwordx4 v[26:27], off
	s_waitcnt vmcnt(4)
	s_barrier
	s_cbranch_vccnz .LBB0_204
	s_waitcnt vmcnt(0)
	v_mov_b32_e32 v26, v15
	v_mov_b32_e32 v27, v16
	v_mov_b32_e32 v15, v17
	v_mov_b32_e32 v16, v11
	v_mov_b32_e32 v17, v12
	v_mov_b32_e32 v11, v13
	v_pk_add_f32 v[14:15], v[26:27], v[14:15]
	v_pk_add_f32 v[10:11], v[16:17], v[10:11]
	v_add_f32_e32 v14, v14, v15
	v_pk_add_f32 v[10:11], v[10:11], v[10:11] op_sel_hi:[0,1]
	v_add_f32_e32 v15, 0, v14
	v_add_f32_e32 v7, v6, v7
	v_add_f32_e32 v9, v8, v9
	v_mov_b32_e32 v6, v2
	v_mov_b32_e32 v8, v3
	v_mov_b32_e32 v10, v4
	v_mov_b32_e32 v14, v5
	v_pk_add_f32 v[2:3], v[6:7], v[8:9]
	v_pk_add_f32 v[4:5], v[10:11], v[14:15]
	s_nop 0
	v_pk_add_f32 v[2:3], v[2:3], v[4:5]
	s_nop 0
	v_add_f32_e32 v2, v2, v3
	v_fmamk_f32 v2, v2, 0x3a800000, v191
	v_mul_f32_e32 v3, 0x4b800000, v2
	v_cmp_gt_f32_e32 vcc, s96, v2
	s_nop 1
	v_cndmask_b32_e32 v2, v2, v3, vcc
	v_rsq_f32_e32 v2, v2
	s_nop 0
	v_mul_f32_e32 v3, 0x45800000, v2
	v_cndmask_b32_e32 v2, v2, v3, vcc
	v_lshl_add_u32 v3, v18, 2, 0
	v_add_u32_e32 v3, 0x20400, v3
	ds_write_b32 v3, v2

.LBB0_211:
	s_add_i32 s73, s58, 2
	s_add_u32 s74, s56, 0x80
	s_addc_u32 s59, s57, 0
	s_add_i32 s78, 0, 0x10000
	s_cmp_eq_u32 s63, s58
	s_cselect_b32 s59, s51, s59
	s_cselect_b32 s58, s55, s74
	v_add_u32_e32 v0, s78, v146
	s_cselect_b32 s75, s45, s72
	s_cselect_b32 s74, s44, s67
	s_add_i32 s80, 0, 0x14000
	ds_read_b128 v[148:151], v0
	ds_read_b128 v[152:155], v0 offset:1024
	ds_read_b128 v[156:159], v0 offset:2048
	ds_read_b128 v[160:163], v0 offset:3072
	v_add_u32_e32 v0, s80, v146
	ds_read_b128 v[164:167], v0
	ds_read_b128 v[168:171], v0 offset:1024
	ds_read_b128 v[172:175], v0 offset:2048
	ds_read_b128 v[176:179], v0 offset:3072
	v_lshl_add_u64 v[142:143], s[56:57], 0, v[136:137]
	s_mov_b32 m0, s31
	ds_read_b128 v[180:183], v147
	ds_read_b128 v[184:187], v147 offset:1024
	ds_read_b128 v[200:203], v147 offset:2048
	ds_read_b128 v[204:207], v147 offset:3072
	ds_read_b128 v[208:211], v147 offset:4096
	ds_read_b128 v[212:215], v147 offset:5120
	ds_read_b128 v[216:219], v147 offset:6144
	ds_read_b128 v[220:223], v147 offset:7168
	global_load_lds_dwordx4 v[142:143], off
	v_lshl_add_u64 v[142:143], s[56:57], 0, v[132:133]
	s_mov_b32 m0, s53
	s_nop 0
	global_load_lds_dwordx4 v[142:143], off
	v_lshl_add_u64 v[142:143], s[56:57], 0, v[138:139]
	s_add_i32 m0, s27, 0xc000
	s_nop 0
	global_load_lds_dwordx4 v[142:143], off
	v_lshl_add_u64 v[142:143], s[56:57], 0, v[140:141]
	s_add_i32 m0, s27, 0xe000
	s_nop 0
	global_load_lds_dwordx4 v[142:143], off
	s_waitcnt vmcnt(8)
	s_waitcnt lgkmcnt(0)
	s_barrier
	s_setprio 1
	s_waitcnt lgkmcnt(0)
	v_mfma_f32_16x16x32_bf16 v[122:125], v[148:151], v[180:183], v[122:125]
	v_mfma_f32_16x16x32_bf16 v[126:129], v[156:159], v[180:183], v[126:129]
	v_mfma_f32_16x16x32_bf16 v[110:113], v[148:151], v[200:203], v[110:113]
	v_mfma_f32_16x16x32_bf16 v[106:109], v[156:159], v[200:203], v[106:109]
	v_mfma_f32_16x16x32_bf16 v[94:97], v[148:151], v[208:211], v[94:97]
	v_mfma_f32_16x16x32_bf16 v[90:93], v[156:159], v[208:211], v[90:93]
	v_mfma_f32_16x16x32_bf16 v[78:81], v[148:151], v[216:219], v[78:81]
	v_mfma_f32_16x16x32_bf16 v[74:77], v[156:159], v[216:219], v[74:77]
	v_mfma_f32_16x16x32_bf16 v[122:125], v[152:155], v[184:187], v[122:125]
	v_mfma_f32_16x16x32_bf16 v[126:129], v[160:163], v[184:187], v[126:129]
	v_mfma_f32_16x16x32_bf16 v[110:113], v[152:155], v[204:207], v[110:113]
	v_mfma_f32_16x16x32_bf16 v[106:109], v[160:163], v[204:207], v[106:109]
	v_mfma_f32_16x16x32_bf16 v[94:97], v[152:155], v[212:215], v[94:97]
	v_mfma_f32_16x16x32_bf16 v[90:93], v[160:163], v[212:215], v[90:93]
	v_mfma_f32_16x16x32_bf16 v[78:81], v[152:155], v[220:223], v[78:81]
	v_mfma_f32_16x16x32_bf16 v[74:77], v[160:163], v[220:223], v[74:77]
	s_setprio 0
	s_setprio 1
	v_mfma_f32_16x16x32_bf16 v[118:121], v[164:167], v[180:183], v[118:121]
	v_mfma_f32_16x16x32_bf16 v[114:117], v[172:175], v[180:183], v[114:117]
	v_mfma_f32_16x16x32_bf16 v[102:105], v[164:167], v[200:203], v[102:105]
	v_mfma_f32_16x16x32_bf16 v[98:101], v[172:175], v[200:203], v[98:101]
	v_mfma_f32_16x16x32_bf16 v[86:89], v[164:167], v[208:211], v[86:89]
	v_mfma_f32_16x16x32_bf16 v[82:85], v[172:175], v[208:211], v[82:85]
	v_mfma_f32_16x16x32_bf16 v[70:73], v[164:167], v[216:219], v[70:73]
	v_mfma_f32_16x16x32_bf16 v[66:69], v[172:175], v[216:219], v[66:69]
	v_mfma_f32_16x16x32_bf16 v[118:121], v[168:171], v[184:187], v[118:121]
	v_mfma_f32_16x16x32_bf16 v[114:117], v[176:179], v[184:187], v[114:117]
	v_mfma_f32_16x16x32_bf16 v[102:105], v[168:171], v[204:207], v[102:105]
	v_mfma_f32_16x16x32_bf16 v[98:101], v[176:179], v[204:207], v[98:101]
	v_mfma_f32_16x16x32_bf16 v[86:89], v[168:171], v[212:215], v[86:89]
	v_mfma_f32_16x16x32_bf16 v[82:85], v[176:179], v[212:215], v[82:85]
	v_mfma_f32_16x16x32_bf16 v[70:73], v[168:171], v[220:223], v[70:73]
	v_mfma_f32_16x16x32_bf16 v[66:69], v[176:179], v[220:223], v[66:69]
	s_setprio 0
	s_barrier
	s_add_i32 s78, s78, s5
	v_lshl_add_u64 v[142:143], s[74:75], 0, v[134:135]
	s_mov_b32 m0, s78
	ds_read_b128 v[180:183], v147 offset:16384
	ds_read_b128 v[184:187], v147 offset:17408
	ds_read_b128 v[200:203], v147 offset:18432
	ds_read_b128 v[204:207], v147 offset:19456
	ds_read_b128 v[208:211], v147 offset:20480
	ds_read_b128 v[212:215], v147 offset:21504
	ds_read_b128 v[216:219], v147 offset:22528
	ds_read_b128 v[220:223], v147 offset:23552
	global_load_lds_dwordx4 v[142:143], off
	s_add_i32 m0, s78, 0x2000
	v_lshl_add_u64 v[188:189], s[74:75], 0, v[130:131]
	s_add_u32 s74, s74, s6
	s_addc_u32 s75, s75, s7
	s_add_i32 s78, s80, s5
	global_load_lds_dwordx4 v[188:189], off
	v_lshl_add_u64 v[224:225], s[74:75], 0, v[134:135]
	s_mov_b32 m0, s78
	v_lshl_add_u64 v[226:227], s[74:75], 0, v[130:131]
	global_load_lds_dwordx4 v[224:225], off
	s_add_i32 m0, s78, 0x2000
	v_lshl_add_u64 v[228:229], s[58:59], 0, v[136:137]
	global_load_lds_dwordx4 v[226:227], off
	v_lshl_add_u64 v[230:231], s[58:59], 0, v[132:133]
	s_waitcnt vmcnt(6)
	s_waitcnt lgkmcnt(0)
	s_barrier
	s_setprio 1
	s_waitcnt lgkmcnt(0)
	v_mfma_f32_16x16x32_bf16 v[62:65], v[148:151], v[180:183], v[62:65]
	v_mfma_f32_16x16x32_bf16 v[58:61], v[156:159], v[180:183], v[58:61]
	v_mfma_f32_16x16x32_bf16 v[46:49], v[148:151], v[200:203], v[46:49]
	v_mfma_f32_16x16x32_bf16 v[42:45], v[156:159], v[200:203], v[42:45]
	v_mfma_f32_16x16x32_bf16 v[30:33], v[148:151], v[208:211], v[30:33]
	v_mfma_f32_16x16x32_bf16 v[26:29], v[156:159], v[208:211], v[26:29]
	v_mfma_f32_16x16x32_bf16 v[14:17], v[148:151], v[216:219], v[14:17]
	v_mfma_f32_16x16x32_bf16 v[10:13], v[156:159], v[216:219], v[10:13]
	v_mfma_f32_16x16x32_bf16 v[62:65], v[152:155], v[184:187], v[62:65]
	v_mfma_f32_16x16x32_bf16 v[58:61], v[160:163], v[184:187], v[58:61]
	v_mfma_f32_16x16x32_bf16 v[46:49], v[152:155], v[204:207], v[46:49]
	v_mfma_f32_16x16x32_bf16 v[42:45], v[160:163], v[204:207], v[42:45]
	v_mfma_f32_16x16x32_bf16 v[30:33], v[152:155], v[212:215], v[30:33]
	v_mfma_f32_16x16x32_bf16 v[26:29], v[160:163], v[212:215], v[26:29]
	v_mfma_f32_16x16x32_bf16 v[14:17], v[152:155], v[220:223], v[14:17]
	v_mfma_f32_16x16x32_bf16 v[10:13], v[160:163], v[220:223], v[10:13]
	s_setprio 0
	s_setprio 1
	v_mfma_f32_16x16x32_bf16 v[54:57], v[164:167], v[180:183], v[54:57]
	v_mfma_f32_16x16x32_bf16 v[50:53], v[172:175], v[180:183], v[50:53]
	v_mfma_f32_16x16x32_bf16 v[38:41], v[164:167], v[200:203], v[38:41]
	v_mfma_f32_16x16x32_bf16 v[34:37], v[172:175], v[200:203], v[34:37]
	v_mfma_f32_16x16x32_bf16 v[22:25], v[164:167], v[208:211], v[22:25]
	v_mfma_f32_16x16x32_bf16 v[18:21], v[172:175], v[208:211], v[18:21]
	v_mfma_f32_16x16x32_bf16 v[6:9], v[164:167], v[216:219], v[6:9]
	v_mfma_f32_16x16x32_bf16 v[2:5], v[172:175], v[216:219], v[2:5]
	v_mfma_f32_16x16x32_bf16 v[54:57], v[168:171], v[184:187], v[54:57]
	v_mfma_f32_16x16x32_bf16 v[50:53], v[176:179], v[184:187], v[50:53]
	v_mfma_f32_16x16x32_bf16 v[38:41], v[168:171], v[204:207], v[38:41]
	v_mfma_f32_16x16x32_bf16 v[34:37], v[176:179], v[204:207], v[34:37]
	v_mfma_f32_16x16x32_bf16 v[22:25], v[168:171], v[212:215], v[22:25]
	v_mfma_f32_16x16x32_bf16 v[18:21], v[176:179], v[212:215], v[18:21]
	v_mfma_f32_16x16x32_bf16 v[6:9], v[168:171], v[220:223], v[6:9]
	v_mfma_f32_16x16x32_bf16 v[2:5], v[176:179], v[220:223], v[2:5]
	s_setprio 0
	s_barrier
	s_add_i32 s74, 0, 0x18000
	v_add_u32_e32 v0, s74, v146
	s_add_i32 s75, 0, 0x1c000
	ds_read_b128 v[148:151], v0
	ds_read_b128 v[152:155], v0 offset:1024
	ds_read_b128 v[156:159], v0 offset:2048
	ds_read_b128 v[160:163], v0 offset:3072
	v_add_u32_e32 v0, s75, v146
	ds_read_b128 v[164:167], v0
	ds_read_b128 v[168:171], v0 offset:1024
	ds_read_b128 v[172:175], v0 offset:2048
	ds_read_b128 v[176:179], v0 offset:3072
	s_add_u32 s58, s58, s2
	s_addc_u32 s59, s59, s3
	s_mov_b32 m0, s27
	v_lshl_add_u64 v[232:233], s[58:59], 0, v[136:137]
	ds_read_b128 v[180:183], v147 offset:32768
	ds_read_b128 v[184:187], v147 offset:33792
	ds_read_b128 v[200:203], v147 offset:34816
	ds_read_b128 v[204:207], v147 offset:35840
	ds_read_b128 v[208:211], v147 offset:36864
	ds_read_b128 v[212:215], v147 offset:37888
	ds_read_b128 v[216:219], v147 offset:38912
	ds_read_b128 v[220:223], v147 offset:39936
	global_load_lds_dwordx4 v[228:229], off
	s_mov_b32 m0, s28
	s_nop 0
	global_load_lds_dwordx4 v[230:231], off
	s_mov_b32 m0, s29
	s_nop 0
	global_load_lds_dwordx4 v[232:233], off
	v_lshl_add_u64 v[232:233], s[58:59], 0, v[132:133]
	s_mov_b32 m0, s30
	s_nop 0
	global_load_lds_dwordx4 v[232:233], off
	s_waitcnt vmcnt(8)
	s_waitcnt lgkmcnt(0)
	s_barrier
	s_setprio 1
	s_waitcnt lgkmcnt(0)
	v_mfma_f32_16x16x32_bf16 v[122:125], v[148:151], v[180:183], v[122:125]
	v_mfma_f32_16x16x32_bf16 v[126:129], v[156:159], v[180:183], v[126:129]
	v_mfma_f32_16x16x32_bf16 v[110:113], v[148:151], v[200:203], v[110:113]
	v_mfma_f32_16x16x32_bf16 v[106:109], v[156:159], v[200:203], v[106:109]
	v_mfma_f32_16x16x32_bf16 v[94:97], v[148:151], v[208:211], v[94:97]
	v_mfma_f32_16x16x32_bf16 v[90:93], v[156:159], v[208:211], v[90:93]
	v_mfma_f32_16x16x32_bf16 v[78:81], v[148:151], v[216:219], v[78:81]
	v_mfma_f32_16x16x32_bf16 v[74:77], v[156:159], v[216:219], v[74:77]
	v_mfma_f32_16x16x32_bf16 v[122:125], v[152:155], v[184:187], v[122:125]
	v_mfma_f32_16x16x32_bf16 v[126:129], v[160:163], v[184:187], v[126:129]
	v_mfma_f32_16x16x32_bf16 v[110:113], v[152:155], v[204:207], v[110:113]
	v_mfma_f32_16x16x32_bf16 v[106:109], v[160:163], v[204:207], v[106:109]
	v_mfma_f32_16x16x32_bf16 v[94:97], v[152:155], v[212:215], v[94:97]
	v_mfma_f32_16x16x32_bf16 v[90:93], v[160:163], v[212:215], v[90:93]
	v_mfma_f32_16x16x32_bf16 v[78:81], v[152:155], v[220:223], v[78:81]
	v_mfma_f32_16x16x32_bf16 v[74:77], v[160:163], v[220:223], v[74:77]
	s_setprio 0
	s_setprio 1
	v_mfma_f32_16x16x32_bf16 v[118:121], v[164:167], v[180:183], v[118:121]
	v_mfma_f32_16x16x32_bf16 v[114:117], v[172:175], v[180:183], v[114:117]
	v_mfma_f32_16x16x32_bf16 v[102:105], v[164:167], v[200:203], v[102:105]
	v_mfma_f32_16x16x32_bf16 v[98:101], v[172:175], v[200:203], v[98:101]
	v_mfma_f32_16x16x32_bf16 v[86:89], v[164:167], v[208:211], v[86:89]
	v_mfma_f32_16x16x32_bf16 v[82:85], v[172:175], v[208:211], v[82:85]
	v_mfma_f32_16x16x32_bf16 v[70:73], v[164:167], v[216:219], v[70:73]
	v_mfma_f32_16x16x32_bf16 v[66:69], v[172:175], v[216:219], v[66:69]
	v_mfma_f32_16x16x32_bf16 v[118:121], v[168:171], v[184:187], v[118:121]
	v_mfma_f32_16x16x32_bf16 v[114:117], v[176:179], v[184:187], v[114:117]
	v_mfma_f32_16x16x32_bf16 v[102:105], v[168:171], v[204:207], v[102:105]
	v_mfma_f32_16x16x32_bf16 v[98:101], v[176:179], v[204:207], v[98:101]
	v_mfma_f32_16x16x32_bf16 v[86:89], v[168:171], v[212:215], v[86:89]
	v_mfma_f32_16x16x32_bf16 v[82:85], v[176:179], v[212:215], v[82:85]
	v_mfma_f32_16x16x32_bf16 v[70:73], v[168:171], v[220:223], v[70:73]
	v_mfma_f32_16x16x32_bf16 v[66:69], v[176:179], v[220:223], v[66:69]
	s_setprio 0
	s_barrier
	s_add_i32 s58, s74, s5
	v_lshl_add_u64 v[142:143], v[142:143], 0, s[24:25]
	s_mov_b32 m0, s58
	ds_read_b128 v[180:183], v147 offset:49152
	ds_read_b128 v[184:187], v147 offset:50176
	ds_read_b128 v[200:203], v147 offset:51200
	ds_read_b128 v[204:207], v147 offset:52224
	ds_read_b128 v[208:211], v147 offset:53248
	ds_read_b128 v[212:215], v147 offset:54272
	ds_read_b128 v[216:219], v147 offset:55296
	ds_read_b128 v[220:223], v147 offset:56320
	global_load_lds_dwordx4 v[142:143], off
	v_lshl_add_u64 v[142:143], v[188:189], 0, s[24:25]
	s_add_i32 m0, s58, 0x2000
	s_add_i32 s58, s75, s5
	global_load_lds_dwordx4 v[142:143], off
	v_lshl_add_u64 v[142:143], v[224:225], 0, s[24:25]
	s_mov_b32 m0, s58
	s_nop 0
	global_load_lds_dwordx4 v[142:143], off
	v_lshl_add_u64 v[142:143], v[226:227], 0, s[24:25]
	s_add_i32 m0, s58, 0x2000
	s_nop 0
	global_load_lds_dwordx4 v[142:143], off
	s_waitcnt vmcnt(6)
	s_waitcnt lgkmcnt(0)
	s_barrier
	s_setprio 1
	s_waitcnt lgkmcnt(0)
	v_mfma_f32_16x16x32_bf16 v[62:65], v[148:151], v[180:183], v[62:65]
	v_mfma_f32_16x16x32_bf16 v[58:61], v[156:159], v[180:183], v[58:61]
	v_mfma_f32_16x16x32_bf16 v[46:49], v[148:151], v[200:203], v[46:49]
	v_mfma_f32_16x16x32_bf16 v[42:45], v[156:159], v[200:203], v[42:45]
	v_mfma_f32_16x16x32_bf16 v[30:33], v[148:151], v[208:211], v[30:33]
	v_mfma_f32_16x16x32_bf16 v[26:29], v[156:159], v[208:211], v[26:29]
	v_mfma_f32_16x16x32_bf16 v[14:17], v[148:151], v[216:219], v[14:17]
	v_mfma_f32_16x16x32_bf16 v[10:13], v[156:159], v[216:219], v[10:13]
	v_mfma_f32_16x16x32_bf16 v[62:65], v[152:155], v[184:187], v[62:65]
	v_mfma_f32_16x16x32_bf16 v[58:61], v[160:163], v[184:187], v[58:61]
	v_mfma_f32_16x16x32_bf16 v[46:49], v[152:155], v[204:207], v[46:49]
	v_mfma_f32_16x16x32_bf16 v[42:45], v[160:163], v[204:207], v[42:45]
	v_mfma_f32_16x16x32_bf16 v[30:33], v[152:155], v[212:215], v[30:33]
	v_mfma_f32_16x16x32_bf16 v[26:29], v[160:163], v[212:215], v[26:29]
	v_mfma_f32_16x16x32_bf16 v[14:17], v[152:155], v[220:223], v[14:17]
	v_mfma_f32_16x16x32_bf16 v[10:13], v[160:163], v[220:223], v[10:13]
	s_setprio 0
	s_setprio 1
	v_mfma_f32_16x16x32_bf16 v[54:57], v[164:167], v[180:183], v[54:57]
	v_mfma_f32_16x16x32_bf16 v[50:53], v[172:175], v[180:183], v[50:53]
	v_mfma_f32_16x16x32_bf16 v[38:41], v[164:167], v[200:203], v[38:41]
	v_mfma_f32_16x16x32_bf16 v[34:37], v[172:175], v[200:203], v[34:37]
	v_mfma_f32_16x16x32_bf16 v[22:25], v[164:167], v[208:211], v[22:25]
	v_mfma_f32_16x16x32_bf16 v[18:21], v[172:175], v[208:211], v[18:21]
	v_mfma_f32_16x16x32_bf16 v[6:9], v[164:167], v[216:219], v[6:9]
	v_mfma_f32_16x16x32_bf16 v[2:5], v[172:175], v[216:219], v[2:5]
	v_mfma_f32_16x16x32_bf16 v[54:57], v[168:171], v[184:187], v[54:57]
	v_mfma_f32_16x16x32_bf16 v[50:53], v[176:179], v[184:187], v[50:53]
	v_mfma_f32_16x16x32_bf16 v[38:41], v[168:171], v[204:207], v[38:41]
	v_mfma_f32_16x16x32_bf16 v[34:37], v[176:179], v[204:207], v[34:37]
	v_mfma_f32_16x16x32_bf16 v[22:25], v[168:171], v[212:215], v[22:25]
	v_mfma_f32_16x16x32_bf16 v[18:21], v[176:179], v[212:215], v[18:21]
	v_mfma_f32_16x16x32_bf16 v[6:9], v[168:171], v[220:223], v[6:9]
	v_mfma_f32_16x16x32_bf16 v[2:5], v[176:179], v[220:223], v[2:5]
	s_setprio 0
	s_barrier
	s_add_u32 s56, s56, 0x100
	s_addc_u32 s57, s57, 0
	s_add_u32 s67, s67, 0x100
	s_addc_u32 s72, s72, 0
	s_cmp_ge_i32 s73, s60
	s_mov_b32 s58, s73
	s_cbranch_scc0 .LBB0_211
	v_readlane_b32 s74, v236, 30
	v_readlane_b32 s75, v236, 31
	v_readlane_b32 s73, v236, 32
	s_mov_b32 s78, s76
